# GEMM mainloop: all LDS-DMAs of next k-tile issued at tile top, barrier moved to tile end (more fetch-latency tolerance)
# speedup vs baseline: 1.1161x; 1.0108x over previous
; #define MFMA32(a, b, c) __builtin_amdgcn_mfma_f32_32x32x16_bf16((a), (b), (c), 0, 0, 0)
; DI unsigned voff256(size_t ld) { const int t = tid512(); return (unsigned)(((size_t)(t >> 3) * ld + (t & 7) * 8) * 2); }
; DI void gemm256(const char* a_u, unsigned a_voff, size_t astep, const char* b_u, unsigned b_voff, size_t bstep, int nk, char* smem, f32x16 (&acc)[4][2]) {
;     ...
;   for (int kt = 0; kt < nk; ++kt) {
;     const int cur = kt & 1, k2 = (kt + 2 < last) ? kt + 2 : last;
;     const char* S = smem + cur * 2 * T2;
;     char* D = smem + (cur ^ 1) * 2 * T2;
;     const char* an = a_u + (size_t)k2 * 128;
;     const char* bn = b_u + (size_t)k2 * 128;
; #pragma unroll
;     for (int s = 0; s < 4; ++s) {
;       bf16x8 a[4], b[2];
; #pragma unroll
;       for (int mi = 0; mi < 4; ++mi) a[mi] = *(const bf16x8*)(S + aoff + mi * 32 * LROW + s * 32);
; #pragma unroll
;       for (int ni = 0; ni < 2; ++ni) b[ni] = *(const bf16x8*)(S + boff + ni * 32 * LROW + s * 32);
;       *(u32x4*)(D + soff + s * 64 * LROW) = ra[s];
;       *(u32x4*)(D + T2 + soff + s * 64 * LROW) = rb[s];
;       ra[s] = *(const u32x4*)(an + s * astep + a_voff);
;       rb[s] = *(const u32x4*)(bn + s * bstep + b_voff);
; #pragma unroll
;       for (int mi = 0; mi < 4; ++mi)
; #pragma unroll
;         for (int ni = 0; ni < 2; ++ni) acc[mi][ni] = MFMA32(a[mi], b[ni], acc[mi][ni]);
;     }
;     __syncthreads();
;   }
; DI void inproj_phase(const Params& p, int layer, char* smem) {
;   const bf16_t* H = (const bf16_t*)(p.ws + O_H);
;   const bf16_t* W = (const bf16_t*)(p.ws + O_WIN) + (size_t)layer * DIN * DM;
;   for (int i = 0;; ++i) {
;     const int L = tile_of(i, 32 * 24);
;     if (L < 0) break;
;     int tm, tn; tile_mn(L, 32, 24, tm, tn);
;     f32x16 acc[4][2]; zero_acc256(acc);
;     gemm256((const char*)(W + (size_t)(tn * 256) * DM), voff256(DM), (size_t)128 * DM, (const char*)(H + (size_t)(256 + tm * 256) * DM), voff256(DM), (size_t)128 * DM, DM / 64, smem, acc);
.Lg_inproj_loop:
	s_add_i32 s56, s56, 1
	s_add_u32 m0, s58, 0x8000
	s_nop 0
	global_load_lds_dwordx4 v164, s[52:53]
	s_add_u32 m0, s58, 0x8400
	s_nop 0
	global_load_lds_dwordx4 v165, s[52:53]
	s_add_u32 m0, s58, 0x8800
	s_nop 0
	global_load_lds_dwordx4 v130, s[52:53]
	s_add_u32 m0, s58, 0x8c00
	s_nop 0
	global_load_lds_dwordx4 v131, s[52:53]
	s_add_u32 m0, s59, 0x8000
	s_nop 0
	global_load_lds_dwordx4 v164, s[54:55]
	s_add_u32 m0, s59, 0x8400
	s_nop 0
	global_load_lds_dwordx4 v165, s[54:55]
	s_add_u32 m0, s59, 0x8800
	s_nop 0
	global_load_lds_dwordx4 v130, s[54:55]
	s_add_u32 m0, s59, 0x8c00
	s_nop 0
	global_load_lds_dwordx4 v131, s[54:55]
	s_waitcnt lgkmcnt(0)
	v_mfma_f32_32x32x16_bf16 v[114:129], v[196:199], v[212:215], v[114:129]
	ds_read_b128 v[220:223], v195 offset:0
	ds_read_b128 v[242:245], v161 offset:0
	v_mfma_f32_32x32x16_bf16 v[50:65], v[196:199], v[216:219], v[50:65]
	ds_read_b128 v[246:249], v161 offset:4096
	ds_read_b128 v[224:227], v195 offset:4096
	v_mfma_f32_32x32x16_bf16 v[98:113], v[200:203], v[212:215], v[98:113]
	ds_read_b128 v[228:231], v195 offset:8192
	ds_read_b128 v[238:241], v195 offset:12288
	v_mfma_f32_32x32x16_bf16 v[34:49], v[200:203], v[216:219], v[34:49]
	v_mfma_f32_32x32x16_bf16 v[82:97], v[204:207], v[212:215], v[82:97]
	v_mfma_f32_32x32x16_bf16 v[18:33], v[204:207], v[216:219], v[18:33]
	v_mfma_f32_32x32x16_bf16 v[66:81], v[208:211], v[212:215], v[66:81]
	v_mfma_f32_32x32x16_bf16 v[2:17], v[208:211], v[216:219], v[2:17]
	s_waitcnt lgkmcnt(0)
	v_mfma_f32_32x32x16_bf16 v[114:129], v[220:223], v[242:245], v[114:129]
	ds_read_b128 v[196:199], v250 offset:0
	ds_read_b128 v[212:215], v162 offset:0
	v_mfma_f32_32x32x16_bf16 v[50:65], v[220:223], v[246:249], v[50:65]
	ds_read_b128 v[216:219], v162 offset:4096
	ds_read_b128 v[200:203], v250 offset:4096
	v_mfma_f32_32x32x16_bf16 v[98:113], v[224:227], v[242:245], v[98:113]
	ds_read_b128 v[204:207], v250 offset:8192
	ds_read_b128 v[208:211], v250 offset:12288
	v_mfma_f32_32x32x16_bf16 v[34:49], v[224:227], v[246:249], v[34:49]
	v_mfma_f32_32x32x16_bf16 v[82:97], v[228:231], v[242:245], v[82:97]
	v_mfma_f32_32x32x16_bf16 v[18:33], v[228:231], v[246:249], v[18:33]
	v_mfma_f32_32x32x16_bf16 v[66:81], v[238:241], v[242:245], v[66:81]
	v_mfma_f32_32x32x16_bf16 v[2:17], v[238:241], v[246:249], v[2:17]
	s_waitcnt lgkmcnt(0)
	v_mfma_f32_32x32x16_bf16 v[114:129], v[196:199], v[212:215], v[114:129]
	ds_read_b128 v[220:223], v251 offset:0
	ds_read_b128 v[242:245], v163 offset:0
	v_mfma_f32_32x32x16_bf16 v[50:65], v[196:199], v[216:219], v[50:65]
	ds_read_b128 v[246:249], v163 offset:4096
	ds_read_b128 v[224:227], v251 offset:4096
	v_mfma_f32_32x32x16_bf16 v[98:113], v[200:203], v[212:215], v[98:113]
	ds_read_b128 v[228:231], v251 offset:8192
	ds_read_b128 v[238:241], v251 offset:12288
	v_mfma_f32_32x32x16_bf16 v[34:49], v[200:203], v[216:219], v[34:49]
	s_cmp_lt_u32 s56, s57
	s_cselect_b32 s60, 0x80, 0
	s_add_u32 s52, s52, s60
	s_addc_u32 s53, s53, 0
	s_add_u32 s54, s54, s60
	s_addc_u32 s55, s55, 0
	v_mfma_f32_32x32x16_bf16 v[82:97], v[204:207], v[212:215], v[82:97]
	v_mfma_f32_32x32x16_bf16 v[18:33], v[204:207], v[216:219], v[18:33]
	v_mfma_f32_32x32x16_bf16 v[66:81], v[208:211], v[212:215], v[66:81]
	v_mfma_f32_32x32x16_bf16 v[2:17], v[208:211], v[216:219], v[2:17]
	s_waitcnt lgkmcnt(0)
	v_mfma_f32_32x32x16_bf16 v[114:129], v[220:223], v[242:245], v[114:129]
	v_mfma_f32_32x32x16_bf16 v[50:65], v[220:223], v[246:249], v[50:65]
	v_mfma_f32_32x32x16_bf16 v[98:113], v[224:227], v[242:245], v[98:113]
	v_mfma_f32_32x32x16_bf16 v[34:49], v[224:227], v[246:249], v[34:49]
	v_mfma_f32_32x32x16_bf16 v[82:97], v[228:231], v[242:245], v[82:97]
	v_mfma_f32_32x32x16_bf16 v[18:33], v[228:231], v[246:249], v[18:33]
	v_mfma_f32_32x32x16_bf16 v[66:81], v[238:241], v[242:245], v[66:81]
	v_mfma_f32_32x32x16_bf16 v[2:17], v[238:241], v[246:249], v[2:17]
	s_waitcnt vmcnt(0)
	s_barrier
; #define MFMA32(a, b, c) __builtin_amdgcn_mfma_f32_32x32x16_bf16((a), (b), (c), 0, 0, 0)
; DI void gemm256(const char* a_u, unsigned a_voff, size_t astep, const char* b_u, unsigned b_voff, size_t bstep, int nk, char* smem, f32x16 (&acc)[4][2]) {
;     ...
;   for (int kt = 0; kt < nk; ++kt) {
;     const int cur = kt & 1, k2 = (kt + 2 < last) ? kt + 2 : last;
;     const char* S = smem + cur * 2 * T2;
;     char* D = smem + (cur ^ 1) * 2 * T2;
;     const char* an = a_u + (size_t)k2 * 128;
;     const char* bn = b_u + (size_t)k2 * 128;
; #pragma unroll
;     for (int s = 0; s < 4; ++s) {
;       bf16x8 a[4], b[2];
; #pragma unroll
;       for (int mi = 0; mi < 4; ++mi) a[mi] = *(const bf16x8*)(S + aoff + mi * 32 * LROW + s * 32);
; #pragma unroll
;       for (int ni = 0; ni < 2; ++ni) b[ni] = *(const bf16x8*)(S + boff + ni * 32 * LROW + s * 32);
;       *(u32x4*)(D + soff + s * 64 * LROW) = ra[s];
;       *(u32x4*)(D + T2 + soff + s * 64 * LROW) = rb[s];
;       ra[s] = *(const u32x4*)(an + s * astep + a_voff);
;       rb[s] = *(const u32x4*)(bn + s * bstep + b_voff);
; #pragma unroll
;       for (int mi = 0; mi < 4; ++mi)
; #pragma unroll
;         for (int ni = 0; ni < 2; ++ni) acc[mi][ni] = MFMA32(a[mi], b[ni], acc[mi][ni]);
;     }
;     __syncthreads();
;   }
	ds_read_b128 v[196:199], v194 offset:32768
	ds_read_b128 v[212:215], v160 offset:32768
	ds_read_b128 v[216:219], v160 offset:36864
	ds_read_b128 v[200:203], v194 offset:36864
	ds_read_b128 v[204:207], v194 offset:40960
	ds_read_b128 v[208:211], v194 offset:45056
	s_add_i32 s56, s56, 1
	s_add_u32 m0, s58, 0x0
	s_nop 0
	global_load_lds_dwordx4 v164, s[52:53]
	s_add_u32 m0, s58, 0x400
	s_nop 0
	global_load_lds_dwordx4 v165, s[52:53]
	s_add_u32 m0, s58, 0x800
	s_nop 0
	global_load_lds_dwordx4 v130, s[52:53]
	s_add_u32 m0, s58, 0xc00
	s_nop 0
	global_load_lds_dwordx4 v131, s[52:53]
	s_add_u32 m0, s59, 0x0
	s_nop 0
	global_load_lds_dwordx4 v164, s[54:55]
	s_add_u32 m0, s59, 0x400
	s_nop 0
	global_load_lds_dwordx4 v165, s[54:55]
	s_add_u32 m0, s59, 0x800
	s_nop 0
	global_load_lds_dwordx4 v130, s[54:55]
	s_add_u32 m0, s59, 0xc00
	s_nop 0
	global_load_lds_dwordx4 v131, s[54:55]
	s_waitcnt lgkmcnt(0)
	v_mfma_f32_32x32x16_bf16 v[114:129], v[196:199], v[212:215], v[114:129]
	ds_read_b128 v[220:223], v195 offset:32768
	ds_read_b128 v[242:245], v161 offset:32768
	v_mfma_f32_32x32x16_bf16 v[50:65], v[196:199], v[216:219], v[50:65]
	ds_read_b128 v[246:249], v161 offset:36864
	ds_read_b128 v[224:227], v195 offset:36864
	v_mfma_f32_32x32x16_bf16 v[98:113], v[200:203], v[212:215], v[98:113]
	ds_read_b128 v[228:231], v195 offset:40960
	ds_read_b128 v[238:241], v195 offset:45056
	v_mfma_f32_32x32x16_bf16 v[34:49], v[200:203], v[216:219], v[34:49]
	v_mfma_f32_32x32x16_bf16 v[82:97], v[204:207], v[212:215], v[82:97]
	v_mfma_f32_32x32x16_bf16 v[18:33], v[204:207], v[216:219], v[18:33]
	v_mfma_f32_32x32x16_bf16 v[66:81], v[208:211], v[212:215], v[66:81]
	v_mfma_f32_32x32x16_bf16 v[2:17], v[208:211], v[216:219], v[2:17]
	s_waitcnt lgkmcnt(0)
	v_mfma_f32_32x32x16_bf16 v[114:129], v[220:223], v[242:245], v[114:129]
	ds_read_b128 v[196:199], v250 offset:32768
	ds_read_b128 v[212:215], v162 offset:32768
	v_mfma_f32_32x32x16_bf16 v[50:65], v[220:223], v[246:249], v[50:65]
	ds_read_b128 v[216:219], v162 offset:36864
	ds_read_b128 v[200:203], v250 offset:36864
	v_mfma_f32_32x32x16_bf16 v[98:113], v[224:227], v[242:245], v[98:113]
	ds_read_b128 v[204:207], v250 offset:40960
	ds_read_b128 v[208:211], v250 offset:45056
	v_mfma_f32_32x32x16_bf16 v[34:49], v[224:227], v[246:249], v[34:49]
	v_mfma_f32_32x32x16_bf16 v[82:97], v[228:231], v[242:245], v[82:97]
	v_mfma_f32_32x32x16_bf16 v[18:33], v[228:231], v[246:249], v[18:33]
	v_mfma_f32_32x32x16_bf16 v[66:81], v[238:241], v[242:245], v[66:81]
	v_mfma_f32_32x32x16_bf16 v[2:17], v[238:241], v[246:249], v[2:17]
	s_waitcnt lgkmcnt(0)
	v_mfma_f32_32x32x16_bf16 v[114:129], v[196:199], v[212:215], v[114:129]
	ds_read_b128 v[220:223], v251 offset:32768
	ds_read_b128 v[242:245], v163 offset:32768
	v_mfma_f32_32x32x16_bf16 v[50:65], v[196:199], v[216:219], v[50:65]
	ds_read_b128 v[246:249], v163 offset:36864
	ds_read_b128 v[224:227], v251 offset:36864
	v_mfma_f32_32x32x16_bf16 v[98:113], v[200:203], v[212:215], v[98:113]
	ds_read_b128 v[228:231], v251 offset:40960
	ds_read_b128 v[238:241], v251 offset:45056
	v_mfma_f32_32x32x16_bf16 v[34:49], v[200:203], v[216:219], v[34:49]
	s_cmp_lt_u32 s56, s57
	s_cselect_b32 s60, 0x80, 0
	s_add_u32 s52, s52, s60
	s_addc_u32 s53, s53, 0
	s_add_u32 s54, s54, s60
	s_addc_u32 s55, s55, 0
	v_mfma_f32_32x32x16_bf16 v[82:97], v[204:207], v[212:215], v[82:97]
	v_mfma_f32_32x32x16_bf16 v[18:33], v[204:207], v[216:219], v[18:33]
	v_mfma_f32_32x32x16_bf16 v[66:81], v[208:211], v[212:215], v[66:81]
	v_mfma_f32_32x32x16_bf16 v[2:17], v[208:211], v[216:219], v[2:17]
	s_waitcnt lgkmcnt(0)
	v_mfma_f32_32x32x16_bf16 v[114:129], v[220:223], v[242:245], v[114:129]
	v_mfma_f32_32x32x16_bf16 v[50:65], v[220:223], v[246:249], v[50:65]
	v_mfma_f32_32x32x16_bf16 v[98:113], v[224:227], v[242:245], v[98:113]
	v_mfma_f32_32x32x16_bf16 v[34:49], v[224:227], v[246:249], v[34:49]
	v_mfma_f32_32x32x16_bf16 v[82:97], v[228:231], v[242:245], v[82:97]
	v_mfma_f32_32x32x16_bf16 v[18:33], v[228:231], v[246:249], v[18:33]
	v_mfma_f32_32x32x16_bf16 v[66:81], v[238:241], v[242:245], v[66:81]
	v_mfma_f32_32x32x16_bf16 v[2:17], v[238:241], v[246:249], v[2:17]
	s_waitcnt vmcnt(0)
	s_barrier
	ds_read_b128 v[196:199], v194 offset:0
	ds_read_b128 v[212:215], v160 offset:0
	ds_read_b128 v[216:219], v160 offset:4096
	ds_read_b128 v[200:203], v194 offset:4096
	ds_read_b128 v[204:207], v194 offset:8192
	ds_read_b128 v[208:211], v194 offset:12288
	s_cmp_lt_u32 s56, s57
	s_cbranch_scc1 .Lg_inproj_loop
	s_waitcnt lgkmcnt(0)
	s_nop 7
	s_nop 7
	s_branch .LBB0_195

; #define MFMA32(a, b, c) __builtin_amdgcn_mfma_f32_32x32x16_bf16((a), (b), (c), 0, 0, 0)
; DI int tid512() { int t = threadIdx.x; asm volatile("" : "+v"(t)); return t; }
; DI unsigned voff256(size_t ld) { const int t = tid512(); return (unsigned)(((size_t)(t >> 3) * ld + (t & 7) * 8) * 2); }
; DI void gemm256(const char* a_u, unsigned a_voff, size_t astep, const char* b_u, unsigned b_voff, size_t bstep, int nk, char* smem, f32x16 (&acc)[4][2]) {
;     ...
;   for (int kt = 0; kt < nk; ++kt) {
;     const int cur = kt & 1, k2 = (kt + 2 < last) ? kt + 2 : last;
;     const char* S = smem + cur * 2 * T2;
;     char* D = smem + (cur ^ 1) * 2 * T2;
;     const char* an = a_u + (size_t)k2 * 128;
;     const char* bn = b_u + (size_t)k2 * 128;
; #pragma unroll
;     for (int s = 0; s < 4; ++s) {
;       bf16x8 a[4], b[2];
; #pragma unroll
;       for (int mi = 0; mi < 4; ++mi) a[mi] = *(const bf16x8*)(S + aoff + mi * 32 * LROW + s * 32);
; #pragma unroll
;       for (int ni = 0; ni < 2; ++ni) b[ni] = *(const bf16x8*)(S + boff + ni * 32 * LROW + s * 32);
;       *(u32x4*)(D + soff + s * 64 * LROW) = ra[s];
;       *(u32x4*)(D + T2 + soff + s * 64 * LROW) = rb[s];
;       ra[s] = *(const u32x4*)(an + s * astep + a_voff);
;       rb[s] = *(const u32x4*)(bn + s * bstep + b_voff);
; #pragma unroll
;       for (int mi = 0; mi < 4; ++mi)
; #pragma unroll
;         for (int ni = 0; ni < 2; ++ni) acc[mi][ni] = MFMA32(a[mi], b[ni], acc[mi][ni]);
;     }
;     __syncthreads();
;   }
; DI void gateup256(const Params& p, int layer, char* smem) {
;     ...
;   for (int i = 0;; ++i) {
;     const int L = tile_of(i, 32 * 44);
;     if (L < 0) break;
;     int tm, nb; tile_mn(L, 32, 44, tm, nb);
;     const int t = tid512(), lane = t & 63, w = t >> 6, wm = w >> 2, wn = w & 3, r = lane & 31, h = lane >> 5;
;     const unsigned bvo = (unsigned)(((size_t)((t >> 3) & 31) * DM + (t & 7) * 8) * 2 + ((((t >> 3) >> 5) & 1) ? (O_WU - O_WG) : 0));
;     f32x16 acc[4][2]; zero_acc256(acc);
;     gemm256((const char*)(H + (size_t)(256 + tm * 256) * DM), voff256(DM), (size_t)128 * DM, (const char*)(WG + (size_t)(nb * 128) * DM), bvo, (size_t)64 * DM, DM / 64, smem, acc);
.Lg_gateup_loop:
	s_add_i32 s56, s56, 1
	s_add_u32 m0, s58, 0x8000
	s_nop 0
	global_load_lds_dwordx4 v164, s[52:53]
	s_add_u32 m0, s58, 0x8400
	s_nop 0
	global_load_lds_dwordx4 v165, s[52:53]
	s_add_u32 m0, s58, 0x8800
	s_nop 0
	global_load_lds_dwordx4 v130, s[52:53]
	s_add_u32 m0, s58, 0x8c00
	s_nop 0
	global_load_lds_dwordx4 v131, s[52:53]
	s_add_u32 m0, s59, 0x8000
	s_nop 0
	global_load_lds_dwordx4 v164, s[54:55]
	s_add_u32 m0, s59, 0x8400
	s_nop 0
	global_load_lds_dwordx4 v165, s[54:55]
	s_add_u32 m0, s59, 0x8800
	s_nop 0
	global_load_lds_dwordx4 v130, s[54:55]
	s_add_u32 m0, s59, 0x8c00
	s_nop 0
	global_load_lds_dwordx4 v131, s[54:55]
	s_waitcnt lgkmcnt(0)
	v_mfma_f32_32x32x16_bf16 v[114:129], v[196:199], v[212:215], v[114:129]
	ds_read_b128 v[220:223], v195 offset:0
	ds_read_b128 v[242:245], v161 offset:0
	v_mfma_f32_32x32x16_bf16 v[98:113], v[196:199], v[216:219], v[98:113]
	ds_read_b128 v[246:249], v161 offset:4096
	ds_read_b128 v[224:227], v195 offset:4096
	v_mfma_f32_32x32x16_bf16 v[82:97], v[200:203], v[212:215], v[82:97]
	ds_read_b128 v[228:231], v195 offset:8192
	ds_read_b128 v[238:241], v195 offset:12288
	v_mfma_f32_32x32x16_bf16 v[66:81], v[200:203], v[216:219], v[66:81]
	v_mfma_f32_32x32x16_bf16 v[50:65], v[204:207], v[212:215], v[50:65]
	v_mfma_f32_32x32x16_bf16 v[34:49], v[204:207], v[216:219], v[34:49]
	v_mfma_f32_32x32x16_bf16 v[18:33], v[208:211], v[212:215], v[18:33]
	v_mfma_f32_32x32x16_bf16 v[2:17], v[208:211], v[216:219], v[2:17]
	s_waitcnt lgkmcnt(0)
	v_mfma_f32_32x32x16_bf16 v[114:129], v[220:223], v[242:245], v[114:129]
	ds_read_b128 v[196:199], v250 offset:0
	ds_read_b128 v[212:215], v162 offset:0
	v_mfma_f32_32x32x16_bf16 v[98:113], v[220:223], v[246:249], v[98:113]
	ds_read_b128 v[216:219], v162 offset:4096
	ds_read_b128 v[200:203], v250 offset:4096
	v_mfma_f32_32x32x16_bf16 v[82:97], v[224:227], v[242:245], v[82:97]
	ds_read_b128 v[204:207], v250 offset:8192
	ds_read_b128 v[208:211], v250 offset:12288
	v_mfma_f32_32x32x16_bf16 v[66:81], v[224:227], v[246:249], v[66:81]
	v_mfma_f32_32x32x16_bf16 v[50:65], v[228:231], v[242:245], v[50:65]
	v_mfma_f32_32x32x16_bf16 v[34:49], v[228:231], v[246:249], v[34:49]
	v_mfma_f32_32x32x16_bf16 v[18:33], v[238:241], v[242:245], v[18:33]
	v_mfma_f32_32x32x16_bf16 v[2:17], v[238:241], v[246:249], v[2:17]
	s_waitcnt lgkmcnt(0)
	v_mfma_f32_32x32x16_bf16 v[114:129], v[196:199], v[212:215], v[114:129]
	ds_read_b128 v[220:223], v251 offset:0
	ds_read_b128 v[242:245], v163 offset:0
	v_mfma_f32_32x32x16_bf16 v[98:113], v[196:199], v[216:219], v[98:113]
	ds_read_b128 v[246:249], v163 offset:4096
	ds_read_b128 v[224:227], v251 offset:4096
	v_mfma_f32_32x32x16_bf16 v[82:97], v[200:203], v[212:215], v[82:97]
	ds_read_b128 v[228:231], v251 offset:8192
	ds_read_b128 v[238:241], v251 offset:12288
	v_mfma_f32_32x32x16_bf16 v[66:81], v[200:203], v[216:219], v[66:81]
	s_cmp_lt_u32 s56, s57
	s_cselect_b32 s60, 0x80, 0
	s_add_u32 s52, s52, s60
	s_addc_u32 s53, s53, 0
	s_add_u32 s54, s54, s60
	s_addc_u32 s55, s55, 0
	v_mfma_f32_32x32x16_bf16 v[50:65], v[204:207], v[212:215], v[50:65]
	v_mfma_f32_32x32x16_bf16 v[34:49], v[204:207], v[216:219], v[34:49]
	v_mfma_f32_32x32x16_bf16 v[18:33], v[208:211], v[212:215], v[18:33]
	v_mfma_f32_32x32x16_bf16 v[2:17], v[208:211], v[216:219], v[2:17]
	s_waitcnt lgkmcnt(0)
	v_mfma_f32_32x32x16_bf16 v[114:129], v[220:223], v[242:245], v[114:129]
	v_mfma_f32_32x32x16_bf16 v[98:113], v[220:223], v[246:249], v[98:113]
	v_mfma_f32_32x32x16_bf16 v[82:97], v[224:227], v[242:245], v[82:97]
	v_mfma_f32_32x32x16_bf16 v[66:81], v[224:227], v[246:249], v[66:81]
	v_mfma_f32_32x32x16_bf16 v[50:65], v[228:231], v[242:245], v[50:65]
	v_mfma_f32_32x32x16_bf16 v[34:49], v[228:231], v[246:249], v[34:49]
	v_mfma_f32_32x32x16_bf16 v[18:33], v[238:241], v[242:245], v[18:33]
	v_mfma_f32_32x32x16_bf16 v[2:17], v[238:241], v[246:249], v[2:17]
	s_waitcnt vmcnt(0)
	s_barrier
; #define MFMA32(a, b, c) __builtin_amdgcn_mfma_f32_32x32x16_bf16((a), (b), (c), 0, 0, 0)
; DI void gemm256(const char* a_u, unsigned a_voff, size_t astep, const char* b_u, unsigned b_voff, size_t bstep, int nk, char* smem, f32x16 (&acc)[4][2]) {
;     ...
;   for (int kt = 0; kt < nk; ++kt) {
;     const int cur = kt & 1, k2 = (kt + 2 < last) ? kt + 2 : last;
;     const char* S = smem + cur * 2 * T2;
;     char* D = smem + (cur ^ 1) * 2 * T2;
;     const char* an = a_u + (size_t)k2 * 128;
;     const char* bn = b_u + (size_t)k2 * 128;
; #pragma unroll
;     for (int s = 0; s < 4; ++s) {
;       bf16x8 a[4], b[2];
; #pragma unroll
;       for (int mi = 0; mi < 4; ++mi) a[mi] = *(const bf16x8*)(S + aoff + mi * 32 * LROW + s * 32);
; #pragma unroll
;       for (int ni = 0; ni < 2; ++ni) b[ni] = *(const bf16x8*)(S + boff + ni * 32 * LROW + s * 32);
;       *(u32x4*)(D + soff + s * 64 * LROW) = ra[s];
;       *(u32x4*)(D + T2 + soff + s * 64 * LROW) = rb[s];
;       ra[s] = *(const u32x4*)(an + s * astep + a_voff);
;       rb[s] = *(const u32x4*)(bn + s * bstep + b_voff);
; #pragma unroll
;       for (int mi = 0; mi < 4; ++mi)
; #pragma unroll
;         for (int ni = 0; ni < 2; ++ni) acc[mi][ni] = MFMA32(a[mi], b[ni], acc[mi][ni]);
;     }
;     __syncthreads();
;   }
	ds_read_b128 v[196:199], v194 offset:32768
	ds_read_b128 v[212:215], v160 offset:32768
	ds_read_b128 v[216:219], v160 offset:36864
	ds_read_b128 v[200:203], v194 offset:36864
	ds_read_b128 v[204:207], v194 offset:40960
	ds_read_b128 v[208:211], v194 offset:45056
	s_add_i32 s56, s56, 1
	s_add_u32 m0, s58, 0x0
	s_nop 0
	global_load_lds_dwordx4 v164, s[52:53]
	s_add_u32 m0, s58, 0x400
	s_nop 0
	global_load_lds_dwordx4 v165, s[52:53]
	s_add_u32 m0, s58, 0x800
	s_nop 0
	global_load_lds_dwordx4 v130, s[52:53]
	s_add_u32 m0, s58, 0xc00
	s_nop 0
	global_load_lds_dwordx4 v131, s[52:53]
	s_add_u32 m0, s59, 0x0
	s_nop 0
	global_load_lds_dwordx4 v164, s[54:55]
	s_add_u32 m0, s59, 0x400
	s_nop 0
	global_load_lds_dwordx4 v165, s[54:55]
	s_add_u32 m0, s59, 0x800
	s_nop 0
	global_load_lds_dwordx4 v130, s[54:55]
	s_add_u32 m0, s59, 0xc00
	s_nop 0
	global_load_lds_dwordx4 v131, s[54:55]
	s_waitcnt lgkmcnt(0)
	v_mfma_f32_32x32x16_bf16 v[114:129], v[196:199], v[212:215], v[114:129]
	ds_read_b128 v[220:223], v195 offset:32768
	ds_read_b128 v[242:245], v161 offset:32768
	v_mfma_f32_32x32x16_bf16 v[98:113], v[196:199], v[216:219], v[98:113]
	ds_read_b128 v[246:249], v161 offset:36864
	ds_read_b128 v[224:227], v195 offset:36864
	v_mfma_f32_32x32x16_bf16 v[82:97], v[200:203], v[212:215], v[82:97]
	ds_read_b128 v[228:231], v195 offset:40960
	ds_read_b128 v[238:241], v195 offset:45056
	v_mfma_f32_32x32x16_bf16 v[66:81], v[200:203], v[216:219], v[66:81]
	v_mfma_f32_32x32x16_bf16 v[50:65], v[204:207], v[212:215], v[50:65]
	v_mfma_f32_32x32x16_bf16 v[34:49], v[204:207], v[216:219], v[34:49]
	v_mfma_f32_32x32x16_bf16 v[18:33], v[208:211], v[212:215], v[18:33]
	v_mfma_f32_32x32x16_bf16 v[2:17], v[208:211], v[216:219], v[2:17]
	s_waitcnt lgkmcnt(0)
	v_mfma_f32_32x32x16_bf16 v[114:129], v[220:223], v[242:245], v[114:129]
	ds_read_b128 v[196:199], v250 offset:32768
	ds_read_b128 v[212:215], v162 offset:32768
	v_mfma_f32_32x32x16_bf16 v[98:113], v[220:223], v[246:249], v[98:113]
	ds_read_b128 v[216:219], v162 offset:36864
	ds_read_b128 v[200:203], v250 offset:36864
	v_mfma_f32_32x32x16_bf16 v[82:97], v[224:227], v[242:245], v[82:97]
	ds_read_b128 v[204:207], v250 offset:40960
	ds_read_b128 v[208:211], v250 offset:45056
	v_mfma_f32_32x32x16_bf16 v[66:81], v[224:227], v[246:249], v[66:81]
	v_mfma_f32_32x32x16_bf16 v[50:65], v[228:231], v[242:245], v[50:65]
	v_mfma_f32_32x32x16_bf16 v[34:49], v[228:231], v[246:249], v[34:49]
	v_mfma_f32_32x32x16_bf16 v[18:33], v[238:241], v[242:245], v[18:33]
	v_mfma_f32_32x32x16_bf16 v[2:17], v[238:241], v[246:249], v[2:17]
	s_waitcnt lgkmcnt(0)
	v_mfma_f32_32x32x16_bf16 v[114:129], v[196:199], v[212:215], v[114:129]
	ds_read_b128 v[220:223], v251 offset:32768
	ds_read_b128 v[242:245], v163 offset:32768
	v_mfma_f32_32x32x16_bf16 v[98:113], v[196:199], v[216:219], v[98:113]
	ds_read_b128 v[246:249], v163 offset:36864
	ds_read_b128 v[224:227], v251 offset:36864
	v_mfma_f32_32x32x16_bf16 v[82:97], v[200:203], v[212:215], v[82:97]
	ds_read_b128 v[228:231], v251 offset:40960
	ds_read_b128 v[238:241], v251 offset:45056
	v_mfma_f32_32x32x16_bf16 v[66:81], v[200:203], v[216:219], v[66:81]
	s_cmp_lt_u32 s56, s57
	s_cselect_b32 s60, 0x80, 0
	s_add_u32 s52, s52, s60
	s_addc_u32 s53, s53, 0
	s_add_u32 s54, s54, s60
	s_addc_u32 s55, s55, 0
	v_mfma_f32_32x32x16_bf16 v[50:65], v[204:207], v[212:215], v[50:65]
	v_mfma_f32_32x32x16_bf16 v[34:49], v[204:207], v[216:219], v[34:49]
	v_mfma_f32_32x32x16_bf16 v[18:33], v[208:211], v[212:215], v[18:33]
	v_mfma_f32_32x32x16_bf16 v[2:17], v[208:211], v[216:219], v[2:17]
	s_waitcnt lgkmcnt(0)
	v_mfma_f32_32x32x16_bf16 v[114:129], v[220:223], v[242:245], v[114:129]
	v_mfma_f32_32x32x16_bf16 v[98:113], v[220:223], v[246:249], v[98:113]
	v_mfma_f32_32x32x16_bf16 v[82:97], v[224:227], v[242:245], v[82:97]
	v_mfma_f32_32x32x16_bf16 v[66:81], v[224:227], v[246:249], v[66:81]
	v_mfma_f32_32x32x16_bf16 v[50:65], v[228:231], v[242:245], v[50:65]
	v_mfma_f32_32x32x16_bf16 v[34:49], v[228:231], v[246:249], v[34:49]
	v_mfma_f32_32x32x16_bf16 v[18:33], v[238:241], v[242:245], v[18:33]
	v_mfma_f32_32x32x16_bf16 v[2:17], v[238:241], v[246:249], v[2:17]
	s_waitcnt vmcnt(0)
	s_barrier
	ds_read_b128 v[196:199], v194 offset:0
	ds_read_b128 v[212:215], v160 offset:0
	ds_read_b128 v[216:219], v160 offset:4096
	ds_read_b128 v[200:203], v194 offset:4096
	ds_read_b128 v[204:207], v194 offset:8192
	ds_read_b128 v[208:211], v194 offset:12288
	s_cmp_lt_u32 s56, s57
	s_cbranch_scc1 .Lg_gateup_loop
	s_waitcnt lgkmcnt(0)
	s_nop 7
	s_nop 7
	s_branch .LBB0_1568
